# P10 final rmsnorm: loop-invariant final_norm gain row loaded once before the row loop instead of four serialized load/wait/store steps per row
# speedup vs baseline: 1.0098x; 1.0098x over previous
.LBB0_1674:
	v_readlane_b32 s0, v245, 35
	v_readlane_b32 s1, v245, 36
	s_cmp_gt_i32 s0, 10
	s_cselect_b64 s[0:1], -1, 0
	s_xor_b64 s[2:3], s[6:7], -1
	s_or_b64 s[0:1], s[0:1], s[2:3]
	s_and_b64 vcc, exec, s[0:1]
	s_cbranch_vccnz .LBB0_1682
	s_movk_i32 s0, 0x4800
	v_ashrrev_i32_e32 v1, 6, v0
	s_waitcnt vmcnt(0)
	v_lshl_add_u32 v16, s96, 3, v1
	v_cmp_gt_i32_e32 vcc, s0, v16
	s_and_saveexec_b64 s[0:1], vcc
	s_cbranch_execz .LBB0_1682
	v_lshlrev_b32_e32 v0, 4, v0
	v_mov_b32_e32 v17, 0
	v_and_b32_e32 v0, 0x3f0, v0
	v_mov_b32_e32 v1, v17
	v_lshl_add_u64 v[2:3], s[34:35], 0, v[0:1]
	s_mov_b64 s[2:3], 0x12500000
	v_lshl_add_u64 v[18:19], v[2:3], 0, s[2:3]
	s_mov_b64 s[2:3], 0x23500000
	v_readlane_b32 s4, v245, 19
	s_load_dword s0, s[60:61], 0xd0
	v_lshl_add_u64 v[20:21], v[2:3], 0, s[2:3]
	v_readlane_b32 s12, v245, 27
	v_readlane_b32 s13, v245, 28
	v_readlane_b32 s14, v245, 29
	v_readlane_b32 s15, v245, 30
	v_readlane_b32 s16, v245, 31
	v_readlane_b32 s17, v245, 32
	v_ashrrev_i32_e32 v3, 31, v16
	v_mov_b32_e32 v2, v16
	v_readlane_b32 s18, v245, 33
	v_readlane_b32 s19, v245, 34
	s_mov_b64 s[12:13], s[16:17]
	v_lshlrev_b64 v[26:27], 10, v[2:3]
	v_lshlrev_b64 v[2:3], 12, v[2:3]
	v_readlane_b32 s5, v245, 20
	s_mov_b64 s[14:15], s[18:19]
	v_or_b32_e32 v2, v2, v0
	v_lshl_add_u64 v[22:23], s[12:13], 0, v[0:1]
	v_lshl_add_u64 v[24:25], s[14:15], 0, v[0:1]
	v_lshl_add_u64 v[0:1], s[34:35], 0, v[2:3]
	s_mov_b64 s[4:5], 0x7c00000
	v_lshl_add_u64 v[28:29], v[0:1], 0, s[4:5]
	v_mbcnt_lo_u32_b32 v0, -1, 0
	s_waitcnt lgkmcnt(0)
	s_lshl_b32 s0, s0, 3
	v_mbcnt_hi_u32_b32 v33, -1, v0
	v_readlane_b32 s6, v245, 21
	v_readlane_b32 s7, v245, 22
	v_readlane_b32 s10, v245, 25
	v_readlane_b32 s11, v245, 26
	s_ashr_i32 s1, s0, 31
	v_and_b32_e32 v0, 64, v33
	s_lshl_b64 s[2:3], s[0:1], 10
	s_lshl_b64 s[4:5], s[0:1], 12
	s_mov_b64 s[6:7], 0
	s_movk_i32 s1, 0x3fff
	s_mov_b32 s10, 0x800000
	s_mov_b32 s11, 0x1000000
	s_mov_b32 s12, 0x1800000
	s_brev_b32 s13, 64
	s_mov_b32 s14, 0x2800000
	s_mov_b32 s15, 0x3000000
	s_mov_b32 s16, 0x3800000
	v_mov_b32_e32 v32, 0x358637bd
	s_movk_i32 s17, 0x47ff
	v_add_u32_e32 v34, 64, v0
	v_xor_b32_e32 v35, 1, v33
	v_xor_b32_e32 v36, 2, v33
	v_xor_b32_e32 v37, 4, v33
	v_xor_b32_e32 v38, 8, v33
	v_xor_b32_e32 v39, 16, v33
	v_xor_b32_e32 v40, 32, v33
	v_readlane_b32 s8, v245, 23
	v_readlane_b32 s9, v245, 24
	global_load_dwordx4 v[170:173], v[22:23], off
	global_load_dwordx4 v[174:177], v[22:23], off offset:1024
	global_load_dwordx4 v[178:181], v[22:23], off offset:2048
	global_load_dwordx4 v[182:185], v[22:23], off offset:3072
	s_branch .LBB0_1678
.LBB0_1677:
	s_or_b64 exec, exec, s[8:9]
	s_waitcnt lgkmcnt(0)
	v_add_f32_e32 v41, v41, v42
	v_fmamk_f32 v41, v41, 0x3a800000, v32
	v_mul_f32_e32 v42, 0x4b800000, v41
	v_cmp_gt_f32_e32 vcc, s10, v41
	v_lshl_add_u64 v[30:31], v[30:31], 2, v[24:25]
	v_add_u32_e32 v16, s0, v16
	v_cndmask_b32_e32 v41, v41, v42, vcc
	v_rsq_f32_e32 v41, v41
	v_lshl_add_u64 v[26:27], v[26:27], 0, s[2:3]
	v_lshl_add_u64 v[28:29], v[28:29], 0, s[4:5]
	v_mul_f32_e32 v42, 0x45800000, v41
	v_cndmask_b32_e32 v42, v41, v42, vcc
	v_pk_mul_f32 v[12:13], v[12:13], v[42:43] op_sel_hi:[1,0]
	v_pk_mul_f32 v[14:15], v[14:15], v[42:43] op_sel_hi:[1,0]
	v_pk_mul_f32 v[10:11], v[10:11], v[42:43] op_sel_hi:[1,0]
	v_pk_mul_f32 v[8:9], v[8:9], v[42:43] op_sel_hi:[1,0]
	v_pk_mul_f32 v[6:7], v[6:7], v[42:43] op_sel_hi:[1,0]
	v_pk_mul_f32 v[4:5], v[4:5], v[42:43] op_sel_hi:[1,0]
	v_cmp_lt_i32_e32 vcc, s17, v16
	v_pk_mul_f32 v[2:3], v[2:3], v[42:43] op_sel_hi:[1,0]
	v_pk_mul_f32 v[0:1], v[0:1], v[42:43] op_sel_hi:[1,0]
	s_or_b64 s[6:7], vcc, s[6:7]
	s_waitcnt vmcnt(0)
	v_pk_mul_f32 v[14:15], v[172:173], v[14:15]
	v_pk_mul_f32 v[12:13], v[170:171], v[12:13]
	global_store_dwordx4 v[30:31], v[12:15], off
	v_pk_mul_f32 v[8:9], v[174:175], v[8:9]
	v_pk_mul_f32 v[10:11], v[176:177], v[10:11]
	global_store_dwordx4 v[30:31], v[8:11], off offset:1024
	v_pk_mul_f32 v[4:5], v[178:179], v[4:5]
	v_pk_mul_f32 v[6:7], v[180:181], v[6:7]
	global_store_dwordx4 v[30:31], v[4:7], off offset:2048
	v_pk_mul_f32 v[0:1], v[182:183], v[0:1]
	v_pk_mul_f32 v[2:3], v[184:185], v[2:3]
	global_store_dwordx4 v[30:31], v[0:3], off offset:3072
	s_andn2_b64 exec, exec, s[6:7]
	s_cbranch_execz .LBB0_1682
